# v12 + GEMM prologue: issue second stage batch before waiting on the first (vmcnt(8) instead of vmcnt(2)+late issue)
# baseline (speedup 1.0000x reference)
.LBB0_67:
	v_readlane_b32 s14, v253, 56
	v_readlane_b32 s15, v253, 57
	v_readlane_b32 s3, v255, 18
	v_mov_b32_e32 v131, v5
	v_lshl_add_u64 v[10:11], s[14:15], 0, v[4:5]
	v_readlane_b32 s4, v253, 52
	s_cmp_eq_u32 s3, 12
	v_lshl_add_u64 v[12:13], s[14:15], 0, v[130:131]
	v_mov_b32_e32 v135, v5
	v_readlane_b32 s5, v253, 53
	s_cselect_b32 s37, 0x2000, 0
	s_add_i32 m0, s30, 0x18000
	v_lshl_add_u64 v[10:11], v[10:11], 0, s[70:71]
	v_lshl_add_u64 v[14:15], s[4:5], 0, v[134:135]
	v_mov_b32_e32 v133, v5
	v_and_b32_e32 v19, 15, v189
	global_load_lds_dwordx4 v[10:11], off
	v_lshl_add_u64 v[10:11], v[12:13], 0, s[70:71]
	s_add_i32 m0, s30, 0x1a000
	s_add_i32 s51, s30, 0x8000
	v_lshl_add_u64 v[16:17], s[4:5], 0, v[132:133]
	s_and_b32 s50, s1, 3
	v_lshl_or_b32 v144, s2, 6, v19
	s_lshl_b32 s1, s2, 13
	global_load_lds_dwordx4 v[10:11], off
	v_lshl_add_u64 v[10:11], v[14:15], 0, s[70:71]
	s_mov_b32 m0, s51
	s_add_i32 s52, s30, 0xa000
	v_readlane_b32 s2, v253, 58
	global_load_lds_dwordx4 v[10:11], off
	v_lshl_add_u64 v[10:11], v[16:17], 0, s[70:71]
	s_mov_b32 m0, s52
	v_readlane_b32 s3, v253, 59
	global_load_lds_dwordx4 v[10:11], off
	s_add_i32 m0, s30, 0x1c000
	v_lshl_add_u64 v[10:11], s[2:3], 0, v[4:5]
	global_load_lds_dwordx4 v[10:11], off
	v_lshl_add_u64 v[10:11], s[2:3], 0, v[130:131]
	s_add_i32 m0, s30, 0x1e000
	v_bfe_u32 v18, v189, 4, 2
	global_load_lds_dwordx4 v[10:11], off
	v_lshlrev_b32_e32 v21, 4, v18
	v_lshl_or_b32 v19, v19, 6, v21
	v_lshlrev_b32_e32 v21, 2, v189
	v_and_b32_e32 v21, 32, v21
	s_movk_i32 s2, 0x2080
	v_bitop3_b32 v22, v19, s1, v21 bitop3:0xde
	s_lshl_b32 s1, s50, 12
	v_lshrrev_b32_e32 v7, 1, v7
	v_mul_lo_u32 v6, v6, s2
	s_mov_b32 s3, 0x20800
	v_bitop3_b32 v145, s1, v19, v21 bitop3:0xf6
	s_cmpk_lt_u32 s0, 0x100
	v_mad_u64_u32 v[6:7], s[0:1], v7, s3, v[6:7]
	v_or_b32_e32 v6, v6, v8
	v_add_lshl_u32 v6, v6, v9, 1
	v_mov_b32_e32 v7, v5
	s_mov_b64 s[6:7], 0x208080
	v_lshl_add_u64 v[136:137], v[6:7], 0, s[6:7]
	v_lshrrev_b32_e32 v6, 1, v0
	v_mul_lo_u32 v0, v1, s2
	v_mad_u64_u32 v[0:1], s[0:1], v6, s3, v[0:1]
	s_waitcnt vmcnt(8)
	s_barrier
	s_waitcnt vmcnt(6)
	v_or_b32_e32 v0, v0, v2
	v_lshlrev_b32_e32 v20, 3, v18
	v_add_lshl_u32 v0, v0, v3, 1
	v_mov_b32_e32 v1, v5
	v_readlane_b32 s16, v253, 46
	v_readlane_b32 s18, v252, 8
	s_mov_b32 s36, 0
	v_lshl_or_b32 v146, s50, 5, v20
	s_cselect_b64 s[48:49], -1, 0
	v_cmp_eq_u32_e64 s[38:39], 0, v18
	s_or_b32 s53, s37, 16
	s_or_b32 s56, s37, 32
	s_or_b32 s57, s37, 48
	s_or_b32 s58, s37, 0x80
	s_or_b32 s59, s37, 0x90
	s_or_b32 s60, s37, 0xa0
	s_or_b32 s61, s37, 0xb0
	v_lshl_add_u64 v[138:139], v[0:1], 0, s[6:7]
	v_add_u32_e32 v147, 0, v22
	v_readlane_b32 s54, v253, 45
	v_readlane_b32 s64, v253, 44
	s_mov_b64 s[0:1], s[4:5]
	v_readlane_b32 s17, v253, 47
	v_readlane_b32 s19, v252, 9
	s_barrier
	s_branch .LBB0_70

.LBB0_114:
	v_lshrrev_b32_e32 v17, 1, v189
	v_readlane_b32 s14, v253, 11
	v_and_b32_e32 v17, 24, v17
	v_readlane_b32 s15, v253, 12
	v_and_b32_e32 v16, 15, v189
	v_lshlrev_b32_e32 v18, 1, v17
	v_lshl_add_u64 v[8:9], s[14:15], 0, v[4:5]
	v_mov_b32_e32 v131, v5
	v_lshl_or_b32 v140, s4, 6, v16
	v_lshl_or_b32 v16, v16, 6, v18
	v_lshlrev_b32_e32 v18, 2, v189
	s_lshl_b32 s3, s3, 5
	v_lshl_add_u64 v[10:11], s[14:15], 0, v[130:131]
	v_mov_b32_e32 v135, v5
	s_lshl_b32 s4, s4, 13
	v_and_b32_e32 v18, 32, v18
	s_and_b32 s3, s3, 0x60
	s_add_i32 m0, s30, 0x18000
	v_lshl_add_u64 v[8:9], v[8:9], 0, s[70:71]
	v_lshl_add_u64 v[12:13], s[0:1], 0, v[134:135]
	v_mov_b32_e32 v133, v5
	v_bitop3_b32 v19, v16, s4, v18 bitop3:0xde
	s_lshl_b32 s4, s3, 7
	global_load_lds_dwordx4 v[8:9], off
	v_lshl_add_u64 v[8:9], v[10:11], 0, s[70:71]
	s_add_i32 m0, s30, 0x1a000
	s_add_i32 s36, s30, 0x8000
	v_lshl_add_u64 v[14:15], s[0:1], 0, v[132:133]
	v_bitop3_b32 v141, s4, v16, v18 bitop3:0xf6
	global_load_lds_dwordx4 v[8:9], off
	v_lshl_add_u64 v[8:9], v[12:13], 0, s[70:71]
	s_mov_b32 m0, s36
	s_add_i32 s37, s30, 0xa000
	v_readlane_b32 s4, v253, 13
	global_load_lds_dwordx4 v[8:9], off
	v_lshl_add_u64 v[8:9], v[14:15], 0, s[70:71]
	s_mov_b32 m0, s37
	v_readlane_b32 s5, v253, 14
	global_load_lds_dwordx4 v[8:9], off
	s_add_i32 m0, s30, 0x1c000
	v_lshl_add_u64 v[8:9], s[4:5], 0, v[4:5]
	global_load_lds_dwordx4 v[8:9], off
	v_lshl_add_u64 v[8:9], s[4:5], 0, v[130:131]
	s_add_i32 m0, s30, 0x1e000
	s_cmpk_lt_u32 s2, 0x100
	global_load_lds_dwordx4 v[8:9], off
	v_lshlrev_b32_e32 v8, 15, v6
	v_and_b32_e32 v8, 0xffff0000, v8
	v_lshl_add_u32 v3, v3, 12, v8
	v_and_b32_e32 v6, 1, v6
	v_lshl_or_b32 v3, v6, 6, v3
	v_lshl_add_u32 v136, v7, 1, v3
	v_lshlrev_b32_e32 v3, 15, v0
	v_and_b32_e32 v3, 0xffff0000, v3
	s_waitcnt vmcnt(8)
	s_barrier
	s_waitcnt vmcnt(6)
	v_lshl_add_u32 v1, v1, 12, v3
	v_and_b32_e32 v0, 1, v0
	v_lshl_or_b32 v0, v0, 6, v1
	s_cselect_b64 s[42:43], -1, 0
	v_or_b32_e32 v142, s3, v17
	v_mov_b32_e32 v137, v5
	v_lshl_add_u32 v138, v2, 1, v0
	v_mov_b32_e32 v139, v5
	s_mov_b32 s50, 0
	v_add_u32_e32 v143, 0, v19
	v_readlane_b32 s52, v253, 8
	v_readlane_b32 s53, v253, 5
	s_barrier
	s_branch .LBB0_117

.LBB0_151:
	v_readlane_b32 s4, v254, 7
	v_readlane_b32 s5, v254, 8
	v_mov_b32_e32 v131, v5
	v_readlane_b32 s14, v254, 3
	v_lshl_add_u64 v[8:9], s[4:5], 0, v[4:5]
	v_lshl_add_u64 v[10:11], s[4:5], 0, v[130:131]
	v_mov_b32_e32 v135, v5
	v_readlane_b32 s15, v254, 4
	s_add_i32 m0, s26, 0x18000
	v_lshl_add_u64 v[8:9], v[8:9], 0, s[70:71]
	v_lshl_add_u64 v[12:13], s[14:15], 0, v[134:135]
	v_mov_b32_e32 v133, v5
	v_and_b32_e32 v17, 15, v189
	global_load_lds_dwordx4 v[8:9], off
	v_lshl_add_u64 v[8:9], v[10:11], 0, s[70:71]
	s_add_i32 m0, s26, 0x1a000
	s_add_i32 s35, s26, 0x8000
	v_lshl_add_u64 v[14:15], s[14:15], 0, v[132:133]
	s_and_b32 s34, s1, 3
	v_lshl_or_b32 v144, s2, 6, v17
	s_lshl_b32 s1, s2, 13
	global_load_lds_dwordx4 v[8:9], off
	v_lshl_add_u64 v[8:9], v[12:13], 0, s[70:71]
	s_mov_b32 m0, s35
	s_add_i32 s36, s26, 0xa000
	v_readlane_b32 s2, v254, 9
	global_load_lds_dwordx4 v[8:9], off
	v_lshl_add_u64 v[8:9], v[14:15], 0, s[70:71]
	s_mov_b32 m0, s36
	v_readlane_b32 s3, v254, 10
	global_load_lds_dwordx4 v[8:9], off
	s_add_i32 m0, s26, 0x1c000
	v_lshl_add_u64 v[8:9], s[2:3], 0, v[4:5]
	global_load_lds_dwordx4 v[8:9], off
	v_lshl_add_u64 v[8:9], s[2:3], 0, v[130:131]
	s_add_i32 m0, s26, 0x1e000
	v_bfe_u32 v16, v189, 4, 2
	global_load_lds_dwordx4 v[8:9], off
	v_lshlrev_b32_e32 v8, 15, v6
	v_and_b32_e32 v8, 0xffff0000, v8
	v_lshl_add_u32 v3, v3, 12, v8
	v_and_b32_e32 v6, 1, v6
	v_lshlrev_b32_e32 v19, 4, v16
	v_lshl_or_b32 v3, v6, 6, v3
	v_lshl_or_b32 v17, v17, 6, v19
	v_lshlrev_b32_e32 v19, 2, v189
	v_lshl_add_u32 v136, v7, 1, v3
	v_lshlrev_b32_e32 v3, 15, v0
	v_and_b32_e32 v19, 32, v19
	v_and_b32_e32 v3, 0xffff0000, v3
	v_bitop3_b32 v20, v17, s1, v19 bitop3:0xde
	s_lshl_b32 s1, s34, 12
	s_waitcnt vmcnt(8)
	s_barrier
	s_waitcnt vmcnt(6)
	v_lshl_add_u32 v1, v1, 12, v3
	v_and_b32_e32 v0, 1, v0
	v_lshlrev_b32_e32 v18, 3, v16
	s_cmpk_lt_u32 s0, 0x100
	v_lshl_or_b32 v0, v0, 6, v1
	v_bitop3_b32 v145, s1, v17, v19 bitop3:0xf6
	v_lshl_or_b32 v146, s34, 5, v18
	s_cselect_b64 s[46:47], -1, 0
	s_mov_b32 s37, 0
	v_cmp_eq_u32_e64 s[38:39], 0, v16
	v_mov_b32_e32 v137, v5
	v_lshl_add_u32 v138, v2, 1, v0
	v_mov_b32_e32 v139, v5
	v_add_u32_e32 v147, 0, v20
	v_readlane_b32 s51, v253, 15
	v_readlane_b32 s52, v253, 60
	s_mov_b64 s[0:1], s[4:5]
	s_barrier
	s_branch .LBB0_154

.LBB0_193:
	v_readlane_b32 s14, v253, 21
	v_readlane_b32 s15, v253, 22
	v_mov_b32_e32 v135, v5
	v_mov_b32_e32 v131, v5
	v_lshl_add_u64 v[0:1], s[14:15], 0, v[4:5]
	v_lshl_add_u64 v[2:3], s[14:15], 0, v[134:135]
	v_lshlrev_b32_e32 v11, 2, v149
	s_add_i32 m0, s27, 0x18000
	v_lshl_add_u64 v[0:1], v[0:1], 0, s[70:71]
	v_lshl_add_u64 v[6:7], s[0:1], 0, v[130:131]
	v_mov_b32_e32 v133, v5
	v_lshl_or_b32 v148, s4, 6, v149
	v_lshl_or_b32 v10, v149, 6, v166
	s_lshl_b32 s4, s4, 13
	v_and_b32_e32 v11, 32, v11
	global_load_lds_dwordx4 v[0:1], off
	v_lshl_add_u64 v[0:1], v[2:3], 0, s[70:71]
	s_add_i32 m0, s27, 0x1a000
	s_add_i32 s35, s27, 0x8000
	v_lshl_add_u64 v[8:9], s[0:1], 0, v[132:133]
	v_bitop3_b32 v10, v10, s4, v11 bitop3:0xde
	global_load_lds_dwordx4 v[0:1], off
	v_lshl_add_u64 v[0:1], v[6:7], 0, s[70:71]
	s_mov_b32 m0, s35
	s_add_i32 s36, s27, 0xa000
	v_readlane_b32 s4, v253, 23
	global_load_lds_dwordx4 v[0:1], off
	v_lshl_add_u64 v[0:1], v[8:9], 0, s[70:71]
	s_mov_b32 m0, s36
	v_readlane_b32 s5, v253, 24
	global_load_lds_dwordx4 v[0:1], off
	s_add_i32 m0, s27, 0x1c000
	v_lshl_add_u64 v[0:1], s[4:5], 0, v[4:5]
	global_load_lds_dwordx4 v[0:1], off
	v_lshl_add_u64 v[0:1], s[4:5], 0, v[134:135]
	s_add_i32 m0, s27, 0x1e000
	s_lshl_b32 s3, s3, 5
	global_load_lds_dwordx4 v[0:1], off
	v_lshlrev_b32_e32 v0, 14, v146
	v_and_b32_e32 v0, 0xffff8000, v0
	v_lshl_add_u32 v0, v147, 11, v0
	v_and_b32_e32 v1, 1, v146
	v_lshl_or_b32 v0, v1, 6, v0
	v_lshl_add_u32 v136, v151, 1, v0
	v_lshlrev_b32_e32 v0, 14, v162
	v_and_b32_e32 v0, 0xffff8000, v0
	s_and_b32 s3, s3, 0x60
	s_waitcnt vmcnt(8)
	s_barrier
	s_waitcnt vmcnt(6)
	v_lshl_add_u32 v0, v163, 11, v0
	v_and_b32_e32 v1, 1, v162
	s_cmpk_lt_u32 s2, 0x100
	v_lshl_or_b32 v0, v1, 6, v0
	v_lshl_or_b32 v168, s3, 7, v167
	s_cselect_b64 s[46:47], -1, 0
	v_or_b32_e32 v170, s3, v150
	v_mov_b32_e32 v137, v5
	v_lshl_add_u32 v138, v164, 1, v0
	v_mov_b32_e32 v139, v5
	s_mov_b32 s37, 0
	v_add_u32_e32 v172, 0, v10
	v_readlane_b32 s51, v253, 15
	v_readlane_b32 s52, v253, 60
	s_barrier
	s_branch .LBB0_196

.LBB0_216:
	v_readlane_b32 s14, v253, 29
	v_readlane_b32 s15, v253, 30
	v_mov_b32_e32 v135, v5
	v_mov_b32_e32 v131, v5
	v_lshl_add_u64 v[0:1], s[14:15], 0, v[4:5]
	v_lshl_add_u64 v[2:3], s[14:15], 0, v[134:135]
	s_add_i32 m0, s27, 0x18000
	v_lshl_add_u64 v[0:1], v[0:1], 0, s[70:71]
	v_lshl_add_u64 v[6:7], s[0:1], 0, v[130:131]
	v_mov_b32_e32 v133, v5
	global_load_lds_dwordx4 v[0:1], off
	v_lshl_add_u64 v[0:1], v[2:3], 0, s[70:71]
	s_add_i32 m0, s27, 0x1a000
	s_add_i32 s35, s27, 0x8000
	v_lshl_add_u64 v[8:9], s[0:1], 0, v[132:133]
	global_load_lds_dwordx4 v[0:1], off
	v_lshl_add_u64 v[0:1], v[6:7], 0, s[70:71]
	s_mov_b32 m0, s35
	s_add_i32 s36, s27, 0xa000
	v_readlane_b32 s6, v253, 31
	global_load_lds_dwordx4 v[0:1], off
	v_lshl_add_u64 v[0:1], v[8:9], 0, s[70:71]
	s_mov_b32 m0, s36
	v_readlane_b32 s7, v253, 32
	global_load_lds_dwordx4 v[0:1], off
	s_add_i32 m0, s27, 0x1c000
	v_lshl_add_u64 v[0:1], s[6:7], 0, v[4:5]
	global_load_lds_dwordx4 v[0:1], off
	v_lshl_add_u64 v[0:1], s[6:7], 0, v[134:135]
	s_add_i32 m0, s27, 0x1e000
	v_lshl_or_b32 v148, s4, 6, v149
	global_load_lds_dwordx4 v[0:1], off
	v_lshlrev_b32_e32 v1, 2, v149
	v_lshl_or_b32 v0, v149, 6, v166
	s_lshl_b32 s4, s4, 13
	v_and_b32_e32 v1, 32, v1
	v_bitop3_b32 v0, v0, s4, v1 bitop3:0xde
	v_lshlrev_b32_e32 v1, 14, v146
	v_and_b32_e32 v1, 0xffff8000, v1
	v_lshl_add_u32 v1, v147, 11, v1
	v_and_b32_e32 v2, 1, v146
	v_lshl_or_b32 v1, v2, 6, v1
	v_lshl_add_u32 v136, v151, 1, v1
	v_lshlrev_b32_e32 v1, 14, v162
	s_lshl_b32 s3, s3, 5
	v_and_b32_e32 v1, 0xffff8000, v1
	s_and_b32 s3, s3, 0x60
	s_waitcnt vmcnt(8)
	s_barrier
	s_waitcnt vmcnt(6)
	v_lshl_add_u32 v1, v163, 11, v1
	v_and_b32_e32 v2, 1, v162
	s_cmpk_lt_u32 s2, 0x100
	v_lshl_or_b32 v1, v2, 6, v1
	v_lshl_or_b32 v149, s3, 7, v167
	s_cselect_b64 s[44:45], -1, 0
	v_or_b32_e32 v150, s3, v150
	v_mov_b32_e32 v137, v5
	v_lshl_add_u32 v138, v164, 1, v1
	v_mov_b32_e32 v139, v5
	s_mov_b32 s37, 0
	v_add_u32_e32 v151, 0, v0
	v_readlane_b32 s51, v253, 15
	v_readlane_b32 s52, v253, 60
	s_barrier
	s_branch .LBB0_219

.LBB0_240:
	v_lshrrev_b32_e32 v17, 1, v189
	v_readlane_b32 s14, v253, 40
	v_and_b32_e32 v17, 24, v17
	v_readlane_b32 s15, v253, 41
	v_and_b32_e32 v16, 15, v189
	v_lshlrev_b32_e32 v18, 1, v17
	v_lshl_add_u64 v[8:9], s[14:15], 0, v[4:5]
	v_mov_b32_e32 v131, v5
	v_lshl_or_b32 v140, s4, 6, v16
	v_lshl_or_b32 v16, v16, 6, v18
	v_lshlrev_b32_e32 v18, 2, v189
	s_lshl_b32 s3, s3, 5
	v_lshl_add_u64 v[10:11], s[14:15], 0, v[130:131]
	v_mov_b32_e32 v135, v5
	s_lshl_b32 s4, s4, 13
	v_and_b32_e32 v18, 32, v18
	s_and_b32 s3, s3, 0x60
	s_add_i32 m0, s27, 0x18000
	v_lshl_add_u64 v[8:9], v[8:9], 0, s[70:71]
	v_lshl_add_u64 v[12:13], s[0:1], 0, v[134:135]
	v_mov_b32_e32 v133, v5
	v_bitop3_b32 v19, v16, s4, v18 bitop3:0xde
	s_lshl_b32 s4, s3, 7
	global_load_lds_dwordx4 v[8:9], off
	v_lshl_add_u64 v[8:9], v[10:11], 0, s[70:71]
	s_add_i32 m0, s27, 0x1a000
	s_add_i32 s35, s27, 0x8000
	v_lshl_add_u64 v[14:15], s[0:1], 0, v[132:133]
	v_bitop3_b32 v141, s4, v16, v18 bitop3:0xf6
	global_load_lds_dwordx4 v[8:9], off
	v_lshl_add_u64 v[8:9], v[12:13], 0, s[70:71]
	s_mov_b32 m0, s35
	s_add_i32 s36, s27, 0xa000
	v_readlane_b32 s4, v253, 42
	global_load_lds_dwordx4 v[8:9], off
	v_lshl_add_u64 v[8:9], v[14:15], 0, s[70:71]
	s_mov_b32 m0, s36
	v_readlane_b32 s5, v253, 43
	global_load_lds_dwordx4 v[8:9], off
	s_add_i32 m0, s27, 0x1c000
	v_lshl_add_u64 v[8:9], s[4:5], 0, v[4:5]
	global_load_lds_dwordx4 v[8:9], off
	v_lshl_add_u64 v[8:9], s[4:5], 0, v[130:131]
	s_add_i32 m0, s27, 0x1e000
	s_cmpk_lt_u32 s2, 0x100
	global_load_lds_dwordx4 v[8:9], off
	v_lshlrev_b32_e32 v8, 15, v6
	v_and_b32_e32 v8, 0xffff0000, v8
	v_lshl_add_u32 v3, v3, 12, v8
	v_and_b32_e32 v6, 1, v6
	v_lshl_or_b32 v3, v6, 6, v3
	v_lshl_add_u32 v136, v7, 1, v3
	v_lshlrev_b32_e32 v3, 15, v0
	v_and_b32_e32 v3, 0xffff0000, v3
	s_waitcnt vmcnt(8)
	s_barrier
	s_waitcnt vmcnt(6)
	v_lshl_add_u32 v1, v1, 12, v3
	v_and_b32_e32 v0, 1, v0
	v_lshl_or_b32 v0, v0, 6, v1
	s_cselect_b64 s[44:45], -1, 0
	v_or_b32_e32 v142, s3, v17
	v_mov_b32_e32 v137, v5
	v_lshl_add_u32 v138, v2, 1, v0
	v_mov_b32_e32 v139, v5
	s_mov_b32 s37, 0
	v_add_u32_e32 v143, 0, v19
	v_readlane_b32 s51, v253, 35
	v_readlane_b32 s52, v253, 33
	s_barrier
	s_branch .LBB0_243

.LBB0_842:
	v_lshl_add_u64 v[8:9], s[0:1], 0, v[4:5]
	v_mov_b32_e32 v135, v5
	s_lshl_b32 s4, s4, 5
	v_lshl_add_u64 v[10:11], s[0:1], 0, v[134:135]
	v_mov_b32_e32 v131, v5
	s_and_b32 s7, s4, 0x60
	s_add_i32 m0, s26, 0x18000
	v_lshl_add_u64 v[8:9], v[8:9], 0, s[70:71]
	v_lshl_add_u64 v[12:13], s[14:15], 0, v[130:131]
	v_mov_b32_e32 v133, v5
	s_lshl_b32 s6, s3, 13
	s_lshl_b32 s8, s7, 7
	global_load_lds_dwordx4 v[8:9], off
	v_lshl_add_u64 v[8:9], v[10:11], 0, s[70:71]
	s_add_i32 m0, s26, 0x1a000
	s_add_i32 s34, s26, 0x8000
	s_add_i32 s35, s26, 0xa000
	v_lshl_add_u64 v[14:15], s[14:15], 0, v[132:133]
	global_load_lds_dwordx4 v[8:9], off
	v_lshl_add_u64 v[8:9], v[12:13], 0, s[70:71]
	s_mov_b32 m0, s34
	s_add_u32 s4, s0, 0x80080
	global_load_lds_dwordx4 v[8:9], off
	v_lshl_add_u64 v[8:9], v[14:15], 0, s[70:71]
	s_mov_b32 m0, s35
	s_addc_u32 s5, s1, 0
	global_load_lds_dwordx4 v[8:9], off
	s_add_i32 m0, s26, 0x1c000
	v_lshl_add_u64 v[8:9], s[4:5], 0, v[4:5]
	global_load_lds_dwordx4 v[8:9], off
	v_lshl_add_u64 v[8:9], s[4:5], 0, v[134:135]
	s_add_i32 m0, s26, 0x1e000
	s_cmpk_lt_u32 s2, 0x100
	global_load_lds_dwordx4 v[8:9], off
	v_lshrrev_b32_e32 v9, 1, v189
	v_and_b32_e32 v9, 24, v9
	v_and_b32_e32 v8, 15, v189
	v_lshlrev_b32_e32 v10, 1, v9
	v_lshl_or_b32 v162, s3, 6, v8
	v_lshl_or_b32 v8, v8, 6, v10
	v_lshlrev_b32_e32 v10, 2, v189
	v_and_b32_e32 v10, 32, v10
	v_bitop3_b32 v11, v8, s6, v10 bitop3:0xde
	v_bitop3_b32 v163, s8, v8, v10 bitop3:0xf6
	v_lshlrev_b32_e32 v8, 15, v0
	v_and_b32_e32 v8, 0xffff0000, v8
	v_lshl_add_u32 v1, v1, 12, v8
	v_and_b32_e32 v0, 1, v0
	v_lshl_or_b32 v0, v0, 6, v1
	v_lshl_add_u32 v136, v2, 1, v0
	v_lshlrev_b32_e32 v0, 15, v3
	v_and_b32_e32 v0, 0xffff0000, v0
	s_waitcnt vmcnt(8)
	s_barrier
	s_waitcnt vmcnt(6)
	v_lshl_add_u32 v0, v6, 12, v0
	v_and_b32_e32 v1, 1, v3
	v_lshl_or_b32 v0, v1, 6, v0
	s_cselect_b64 s[48:49], -1, 0
	v_or_b32_e32 v164, s7, v9
	v_mov_b32_e32 v137, v5
	v_lshl_add_u32 v138, v7, 1, v0
	v_mov_b32_e32 v139, v5
	s_mov_b32 s36, 0
	v_add_u32_e32 v166, 0, v11
	s_barrier
	s_branch .LBB0_845
